# v30 + software prefetch of the residual base tile (one dword per 128B line) into L2/MALL late in the P4 and P11 K loops
# baseline (speedup 1.0000x reference)
; template <class Epi, class Sched, bool ALIGN_EPI = false, bool SP2 = false>
; __device__ __forceinline__ void gemm_phase(PG8_LAS unsigned char* lds, const Gemm g, const Sched& S, const Epi& E) {
;     ...
;         for (int t = 0; t < nt; t += 2) {
;             const bool last = (t == nt - 2);
;     __device__ __forceinline__ void operator()(const f32x4 (&acc)[2][2][4][2], const Unit& u, int wr, int wc, int fr, int fq) const {
;     ...
;                 const int row = row0 + ai * 128 + m * 16; const size_t off = (size_t)row * D + col0;
;                 float s = 0.f;
; #pragma unroll
;                 for (int bj = 0; bj < 2; ++bj)
; #pragma unroll
;                     for (int n = 0; n < 2; ++n) { const f32x4 b = *(const f32x4*)(base + off + bj * 128 + n * 16); const f32x4 o = b + acc[ai][bj][m][n];
.LBB0_643:
	s_cmp_lg_u32 s96, 12
	s_cbranch_scc1 .Lpf_p4_skip
	s_lshl_b32 s98, s66, 21
	s_lshl_b32 s99, s68, 10
	s_add_u32 s98, s98, s99
	v_and_b32_e32 v248, 0x1f8, v0
	v_and_b32_e32 v249, 7, v0
	v_lshlrev_b32_e32 v248, 10, v248
	v_lshl_or_b32 v248, v249, 7, v248
	v_add_u32_e32 v248, s98, v248
	global_load_dword v249, v248, s[42:43]
	v_add_u32_e32 v248, 0x80000, v248
	global_load_dword v249, v248, s[42:43]
	v_add_u32_e32 v248, 0x80000, v248
	global_load_dword v249, v248, s[42:43]
	v_add_u32_e32 v248, 0x80000, v248
	global_load_dword v249, v248, s[42:43]

; template <class Epi, class Sched, bool ALIGN_EPI = false, bool SP2 = false>
; __device__ __forceinline__ void gemm_phase(PG8_LAS unsigned char* lds, const Gemm g, const Sched& S, const Epi& E) {
;     ...
;         for (int t = 0; t < nt; t += 2) {
;             const bool last = (t == nt - 2);
;     __device__ __forceinline__ void operator()(const f32x4 (&acc)[2][2][4][2], const Unit& u, int wr, int wc, int fr, int fq) const {
;     ...
;                 const size_t off = (size_t)(row0 + ai * 128 + m * 16) * D + col0;
; #pragma unroll
;                 for (int bj = 0; bj < 2; ++bj)
; #pragma unroll
;                     for (int n = 0; n < 2; ++n) { const f32x4 b = *(const f32x4*)(base + off + bj * 128 + n * 16); *(f32x4*)(out + off + bj * 128 + n * 16) = b + acc[ai][bj][m][n]; }
.LBB0_1090:
	s_cmp_lg_u32 s54, 70
	s_cbranch_scc1 .Lpf_p11_skip
	s_lshl_b32 s98, s73, 21
	s_lshl_b32 s99, s74, 10
	s_add_u32 s98, s98, s99
	v_and_b32_e32 v248, 0x1f8, v0
	v_and_b32_e32 v249, 7, v0
	v_lshlrev_b32_e32 v248, 10, v248
	v_lshl_or_b32 v248, v249, 7, v248
	v_add_u32_e32 v248, s98, v248
	global_load_dword v249, v248, s[12:13]
	v_add_u32_e32 v248, 0x80000, v248
	global_load_dword v249, v248, s[12:13]
	v_add_u32_e32 v248, 0x80000, v248
	global_load_dword v249, v248, s[12:13]
	v_add_u32_e32 v248, 0x80000, v248
	global_load_dword v249, v248, s[12:13]
